# E51a: layer-1 memory-attention unit: K/V prefetch distance 1->2 tiles (tile 1 requested in the prologue, tile t+2 at the top of iteration t, two landing sets by parity, vmcnt(4) stage-in wait); on E41
# baseline (speedup 1.0000x reference)
.LBB0_1240:
	s_lshl_b64 s[6:7], s[22:23], 10
	s_add_u32 s6, s51, s6
	s_addc_u32 s7, s58, s7
	s_lshl_b64 s[24:25], s[20:21], 1
	s_add_u32 s34, s6, s24
	s_addc_u32 s35, s7, s25
	s_mov_b64 s[20:21], -1
	s_and_b64 vcc, exec, s[18:19]
	s_cbranch_vccz .LBB0_1317
	s_getreg_b32 s6, hwreg(HW_REG_HW_ID, 0, 6)
	s_and_b32 s6, s6, 63
	s_lshl_b32 s6, s6, 2
	s_add_i32 s6, s6, 0
	s_add_i32 s8, s6, 0x23e00
	s_mov_b64 s[6:7], src_shared_base
	v_mov_b32_e32 v4, s8
	v_mov_b32_e32 v5, s7
	flat_load_dword v2, v[4:5] sc0 sc1
	s_waitcnt vmcnt(0)
	s_add_i32 s7, s3, -1
	v_mov_b32_e32 v153, v3
	v_mov_b32_e32 v158, 0xf149f2ca
	s_mov_b64 s[36:37], 0
	s_waitcnt lgkmcnt(0)
	v_readfirstlane_b32 s6, v2
	s_nop 1
	v_lshl_add_u32 v28, s6, 6, v217
	v_ashrrev_i32_e32 v2, 31, v28
	v_readfirstlane_b32 s6, v28
	s_ashr_i32 s6, s6, 1
	s_andn2_b32 s6, s6, 31
	v_add_u32_e32 v12, 0x200, v28
	v_or_b32_e32 v156, s6, v212
	v_lshrrev_b32_e32 v2, 28, v2
	v_ashrrev_i32_e32 v13, 31, v12
	v_min_i32_e32 v4, s7, v156
	v_add_u32_e32 v2, v28, v2
	v_lshrrev_b32_e32 v13, 28, v13
	v_ashrrev_i32_e32 v5, 31, v4
	v_ashrrev_i32_e32 v20, 4, v2
	v_and_b32_e32 v2, -16, v2
	v_add_u32_e32 v13, v12, v13
	v_lshlrev_b64 v[4:5], 10, v[4:5]
	v_sub_u32_e32 v2, v28, v2
	v_ashrrev_i32_e32 v24, 4, v13
	v_and_b32_e32 v13, -16, v13
	v_lshl_add_u64 v[4:5], s[34:35], 0, v[4:5]
	v_lshlrev_b32_e32 v22, 3, v2
	v_sub_u32_e32 v29, v12, v13
	v_lshl_add_u64 v[4:5], v[4:5], 0, v[152:153]
	v_ashrrev_i32_e32 v23, 31, v22
	v_lshlrev_b32_e32 v26, 3, v29
	global_load_dwordx4 v[142:145], v[4:5], off
	global_load_dwordx4 v[138:141], v[4:5], off offset:32
	global_load_dwordx4 v[134:137], v[4:5], off offset:64
	global_load_dwordx4 v[130:133], v[4:5], off offset:96
	global_load_dwordx4 v[126:129], v[4:5], off offset:128
	global_load_dwordx4 v[122:125], v[4:5], off offset:160
	global_load_dwordx4 v[118:121], v[4:5], off offset:192
	global_load_dwordx4 v[114:117], v[4:5], off offset:224
	v_mad_i64_i32 v[4:5], s[8:9], s30, v20, v[22:23]
	v_ashrrev_i32_e32 v27, 31, v26
	v_lshlrev_b64 v[8:9], 1, v[4:5]
	v_mad_i64_i32 v[12:13], s[8:9], s30, v24, v[26:27]
	v_lshl_add_u64 v[4:5], s[26:27], 0, v[8:9]
	v_lshlrev_b64 v[16:17], 1, v[12:13]
	global_load_dwordx4 v[4:7], v[4:5], off
	v_lshl_add_u64 v[8:9], s[28:29], 0, v[8:9]
	v_lshl_add_u64 v[12:13], s[26:27], 0, v[16:17]
	global_load_dwordx4 v[8:11], v[8:9], off
	v_lshl_add_u64 v[16:17], s[28:29], 0, v[16:17]
	global_load_dwordx4 v[12:15], v[12:13], off
	v_mul_lo_u32 v192, v20, s71
	global_load_dwordx4 v[16:19], v[16:17], off
	v_lshlrev_b32_e32 v193, 4, v2
	v_add3_u32 v2, 0, v192, v193
	v_mul_lo_u32 v195, v24, s71
	v_lshlrev_b32_e32 v196, 4, v29
	s_barrier
	v_ashrrev_i32_e32 v25, 31, v24
	s_cmp_lt_i32 s6, s3
	s_cselect_b64 s[20:21], -1, 0
	s_lshl_b32 s10, s30, 1
	v_ashrrev_i32_e32 v21, 31, v20
	v_mul_lo_u32 v194, v20, s70
	v_mul_lo_u32 v197, v24, s70
	s_lshl_b32 s7, s30, 7
	v_mov_b32_e32 v153, 0
	s_waitcnt vmcnt(3)
	ds_write_b128 v2, v[4:7]
	v_mad_u64_u32 v[4:5], s[8:9], v20, 48, v[2:3]
	v_add3_u32 v2, 0, v195, v196
	s_waitcnt vmcnt(2)
	ds_write_b128 v4, v[8:11] offset:17408
	s_waitcnt vmcnt(1)
	ds_write_b128 v2, v[12:15]
	v_mad_u64_u32 v[4:5], s[8:9], v24, 48, v[2:3]
	v_lshrrev_b32_e32 v2, 2, v28
	s_waitcnt vmcnt(0)
	ds_write_b128 v4, v[16:19] offset:17408
	v_and_or_b32 v4, v2, 3, v216
	v_mul_u32_u24_e32 v191, 0x140, v4
	v_lshl_add_u64 v[4:5], v[24:25], 0, 64
	v_lshlrev_b64 v[6:7], 1, v[26:27]
	v_mad_u64_u32 v[6:7], s[8:9], s10, v4, v[6:7]
	v_mad_i32_i24 v7, s10, v5, v7
	v_lshl_add_u64 v[160:161], s[26:27], 0, v[6:7]
	v_lshl_add_u64 v[162:163], s[28:29], 0, v[6:7]
	v_lshl_add_u64 v[4:5], v[20:21], 0, 64
	v_lshlrev_b64 v[6:7], 1, v[22:23]
	v_mad_u64_u32 v[6:7], s[8:9], s10, v4, v[6:7]
	v_and_or_b32 v2, v2, 4, v225
	v_mad_i32_i24 v7, s10, v5, v7
	v_mov_b32_e32 v16, v3
	v_mov_b32_e32 v17, v3
	v_lshlrev_b32_e32 v157, 3, v2
	v_lshl_add_u64 v[164:165], s[26:27], 0, v[6:7]
	v_lshl_add_u64 v[166:167], s[28:29], 0, v[6:7]
	global_load_dwordx4 v[226:229], v[164:165], off
	global_load_dwordx4 v[230:233], v[166:167], off
	global_load_dwordx4 v[234:237], v[160:161], off
	global_load_dwordx4 v[238:241], v[162:163], off
	v_mov_b32_e32 v2, v3
	v_mov_b32_e32 v4, v3
	v_mov_b32_e32 v5, v3
	v_mov_b32_e32 v6, v3
	v_mov_b32_e32 v7, v3
	v_mov_b32_e32 v8, v3
	v_mov_b32_e32 v9, v3
	v_mov_b32_e32 v10, v3
	v_mov_b32_e32 v11, v3
	v_mov_b32_e32 v12, v3
	v_mov_b32_e32 v13, v3
	v_mov_b32_e32 v14, v3
	v_mov_b32_e32 v15, v3
	v_mov_b64_e32 v[32:33], v[16:17]
	v_mov_b64_e32 v[48:49], v[16:17]
	v_mov_b64_e32 v[64:65], v[16:17]
	v_mov_b64_e32 v[80:81], v[16:17]
	s_mov_b32 s8, 0
	v_mov_b64_e32 v[30:31], v[14:15]
	v_mov_b64_e32 v[28:29], v[12:13]
	v_mov_b64_e32 v[26:27], v[10:11]
	v_mov_b64_e32 v[24:25], v[8:9]
	v_mov_b64_e32 v[22:23], v[6:7]
	v_mov_b64_e32 v[20:21], v[4:5]
	v_mov_b64_e32 v[18:19], v[2:3]
	v_mov_b64_e32 v[46:47], v[14:15]
	v_mov_b64_e32 v[44:45], v[12:13]
	v_mov_b64_e32 v[42:43], v[10:11]
	v_mov_b64_e32 v[40:41], v[8:9]
	v_mov_b64_e32 v[38:39], v[6:7]
	v_mov_b64_e32 v[36:37], v[4:5]
	v_mov_b64_e32 v[34:35], v[2:3]
	v_mov_b64_e32 v[62:63], v[14:15]
	v_mov_b64_e32 v[60:61], v[12:13]
	v_mov_b64_e32 v[58:59], v[10:11]
	v_mov_b64_e32 v[56:57], v[8:9]
	v_mov_b64_e32 v[54:55], v[6:7]
	v_mov_b64_e32 v[52:53], v[4:5]
	v_mov_b64_e32 v[50:51], v[2:3]
	v_mov_b64_e32 v[78:79], v[14:15]
	v_mov_b64_e32 v[76:77], v[12:13]
	v_mov_b64_e32 v[74:75], v[10:11]
	v_mov_b64_e32 v[72:73], v[8:9]
	v_mov_b64_e32 v[70:71], v[6:7]
	v_mov_b64_e32 v[68:69], v[4:5]
	v_mov_b64_e32 v[66:67], v[2:3]
	s_waitcnt lgkmcnt(0)
	s_barrier
	s_branch .LBB0_1244

.LBB0_1243:
	s_add_i32 s8, s8, 1
	s_bitcmp1_b32 s8, 0
	s_cselect_b32 s9, 0x9400, 0
	s_add_i32 s9, s9, 0
	s_add_u32 s36, s36, s7
	s_addc_u32 s37, s37, 0
	s_cmp_lt_u32 s8, 3
	s_cbranch_scc1 .LmdL1_w4
	s_waitcnt vmcnt(0)
	s_branch .LmdL1_wd

.LmdL1_wd:
	s_bitcmp1_b32 s8, 0
	s_cbranch_scc1 .LmdL1_wB
	v_add3_u32 v2, s9, v192, v193
	ds_write_b128 v2, v[4:7]
	v_add3_u32 v2, s9, v194, v193
	ds_write_b128 v2, v[8:11] offset:17408
	v_add3_u32 v2, s9, v195, v196
	ds_write_b128 v2, v[12:15]
	v_add3_u32 v2, s9, v197, v196
	ds_write_b128 v2, v[146:149] offset:17408
	s_branch .LmdL1_wj
.LmdL1_wB:
	v_add3_u32 v2, s9, v192, v193
	ds_write_b128 v2, v[226:229]
	v_add3_u32 v2, s9, v194, v193
	ds_write_b128 v2, v[230:233] offset:17408
	v_add3_u32 v2, s9, v195, v196
	ds_write_b128 v2, v[234:237]
	v_add3_u32 v2, s9, v197, v196
	ds_write_b128 v2, v[238:241] offset:17408
.LmdL1_wj:
	s_cmp_eq_u32 s8, 3
	s_waitcnt lgkmcnt(0)
	s_barrier
	s_cbranch_scc1 .LBB0_1247
.LBB0_1244:
	s_cmp_gt_u32 s8, 1
	s_cbranch_scc1 .LmdL1_nl
	s_add_u32 s98, s36, s7
	s_addc_u32 s99, s37, 0
	s_bitcmp1_b32 s8, 0
	s_cbranch_scc1 .LmdL1_gB
	v_lshl_add_u64 v[242:243], v[164:165], 0, s[98:99]
	global_load_dwordx4 v[4:7], v[242:243], off
	v_lshl_add_u64 v[242:243], v[166:167], 0, s[98:99]
	global_load_dwordx4 v[8:11], v[242:243], off
	v_lshl_add_u64 v[242:243], v[160:161], 0, s[98:99]
	global_load_dwordx4 v[12:15], v[242:243], off
	v_lshl_add_u64 v[242:243], v[162:163], 0, s[98:99]
	global_load_dwordx4 v[146:149], v[242:243], off
	s_branch .LmdL1_nl
.LmdL1_gB:
	v_lshl_add_u64 v[242:243], v[164:165], 0, s[98:99]
	global_load_dwordx4 v[226:229], v[242:243], off
	v_lshl_add_u64 v[242:243], v[166:167], 0, s[98:99]
	global_load_dwordx4 v[230:233], v[242:243], off
	v_lshl_add_u64 v[242:243], v[160:161], 0, s[98:99]
	global_load_dwordx4 v[234:237], v[242:243], off
	v_lshl_add_u64 v[242:243], v[162:163], 0, s[98:99]
	global_load_dwordx4 v[238:241], v[242:243], off
.LmdL1_nl:
	v_cndmask_b32_e64 v2, 0, 1, s[20:21]
	v_cmp_ne_u32_e64 s[18:19], 1, v2
	s_andn2_b64 vcc, exec, s[20:21]
	s_cbranch_vccnz .LBB0_1243
	s_bitcmp1_b32 s8, 0
	s_cselect_b32 s9, 0x9400, 0
	s_add_i32 s9, s9, 0
	v_add3_u32 v2, s9, v214, v159
	ds_read_b128 v[82:85], v2
	ds_read_b128 v[98:101], v2 offset:32
	s_waitcnt lgkmcnt(1)
	v_mfma_f32_32x32x16_bf16 v[82:97], v[82:85], v[142:145], 0
	ds_read_b128 v[168:171], v2 offset:8736
	s_waitcnt lgkmcnt(1)
	v_mfma_f32_32x32x16_bf16 v[82:97], v[98:101], v[138:141], v[82:97]
	ds_read_b128 v[98:101], v2 offset:64
	s_waitcnt lgkmcnt(0)
	v_mfma_f32_32x32x16_bf16 v[82:97], v[98:101], v[134:137], v[82:97]
	ds_read_b128 v[98:101], v2 offset:96
	s_waitcnt lgkmcnt(0)
	v_mfma_f32_32x32x16_bf16 v[82:97], v[98:101], v[130:133], v[82:97]
	ds_read_b128 v[98:101], v2 offset:128
	s_waitcnt lgkmcnt(0)
	v_mfma_f32_32x32x16_bf16 v[82:97], v[98:101], v[126:129], v[82:97]
	ds_read_b128 v[98:101], v2 offset:160
	s_waitcnt lgkmcnt(0)
	v_mfma_f32_32x32x16_bf16 v[82:97], v[98:101], v[122:125], v[82:97]
	ds_read_b128 v[98:101], v2 offset:192
	s_waitcnt lgkmcnt(0)
	v_mfma_f32_32x32x16_bf16 v[82:97], v[98:101], v[118:121], v[82:97]
	ds_read_b128 v[98:101], v2 offset:224
	s_waitcnt lgkmcnt(0)
	v_mfma_f32_32x32x16_bf16 v[82:97], v[98:101], v[114:117], v[82:97]
	ds_read_b128 v[98:101], v2 offset:8704
	s_waitcnt lgkmcnt(0)
	v_mfma_f32_32x32x16_bf16 v[98:113], v[98:101], v[142:145], 0
	v_mfma_f32_32x32x16_bf16 v[98:113], v[168:171], v[138:141], v[98:113]
	ds_read_b128 v[168:171], v2 offset:8768
	s_waitcnt lgkmcnt(0)
	v_mfma_f32_32x32x16_bf16 v[98:113], v[168:171], v[134:137], v[98:113]
	ds_read_b128 v[168:171], v2 offset:8800
	s_waitcnt lgkmcnt(0)
	v_mfma_f32_32x32x16_bf16 v[98:113], v[168:171], v[130:133], v[98:113]
	ds_read_b128 v[168:171], v2 offset:8832
	s_waitcnt lgkmcnt(0)
	v_mfma_f32_32x32x16_bf16 v[98:113], v[168:171], v[126:129], v[98:113]
	ds_read_b128 v[168:171], v2 offset:8864
	s_waitcnt lgkmcnt(0)
	v_mfma_f32_32x32x16_bf16 v[98:113], v[168:171], v[122:125], v[98:113]
	ds_read_b128 v[168:171], v2 offset:8896
	s_waitcnt lgkmcnt(0)
	v_mfma_f32_32x32x16_bf16 v[98:113], v[168:171], v[118:121], v[98:113]
	ds_read_b128 v[168:171], v2 offset:8928
	v_max3_f32 v2, v82, v83, v84
	v_max3_f32 v2, v2, v85, v86
	v_max3_f32 v2, v2, v87, v88
	v_max3_f32 v2, v2, v89, v90
	v_max3_f32 v2, v2, v91, v92
	v_max3_f32 v2, v2, v93, v94
	s_waitcnt lgkmcnt(0)
	v_mfma_f32_32x32x16_bf16 v[98:113], v[168:171], v[114:117], v[98:113]
	v_max3_f32 v2, v2, v95, v96
	s_nop 10
	v_max_f32_e32 v16, v99, v99
	v_max_f32_e32 v17, v98, v98
	v_max_f32_e32 v16, v17, v16
	v_max3_f32 v16, v16, v100, v101
	v_max3_f32 v16, v16, v102, v103
	v_max3_f32 v16, v16, v104, v105
	v_max3_f32 v16, v16, v106, v107
	v_max3_f32 v16, v16, v108, v109
	v_max3_f32 v16, v16, v110, v111
	v_max3_f32 v16, v16, v112, v113
	v_max3_f32 v2, v2, v97, v16
	v_mov_b32_e32 v16, v2
	s_nop 1
	v_permlane32_swap_b32_e32 v2, v16
	v_max_f32_e32 v16, v16, v16
	v_max_f32_e32 v2, v2, v2
	v_max_f32_e32 v2, v2, v16
	v_add_f32_e32 v16, 0x41a00000, v158
	v_cmp_gt_f32_e32 vcc, v2, v16
	s_cbranch_vccz .LBB0_1242
	v_max_f32_e32 v2, v2, v2
	v_max_f32_e32 v16, v158, v158
	v_max_f32_e32 v16, v16, v2
	v_sub_f32_e32 v2, v158, v16
	v_exp_f32_e32 v2, v2
	v_mov_b32_e32 v158, v16
	v_pk_mul_f32 v[80:81], v[80:81], v[2:3] op_sel_hi:[1,0]
	v_pk_mul_f32 v[78:79], v[78:79], v[2:3] op_sel_hi:[1,0]
	v_pk_mul_f32 v[76:77], v[76:77], v[2:3] op_sel_hi:[1,0]
	v_pk_mul_f32 v[74:75], v[74:75], v[2:3] op_sel_hi:[1,0]
	v_pk_mul_f32 v[72:73], v[72:73], v[2:3] op_sel_hi:[1,0]
	v_pk_mul_f32 v[70:71], v[70:71], v[2:3] op_sel_hi:[1,0]
	v_pk_mul_f32 v[68:69], v[68:69], v[2:3] op_sel_hi:[1,0]
	v_pk_mul_f32 v[66:67], v[66:67], v[2:3] op_sel_hi:[1,0]
	v_pk_mul_f32 v[64:65], v[64:65], v[2:3] op_sel_hi:[1,0]
	v_pk_mul_f32 v[62:63], v[62:63], v[2:3] op_sel_hi:[1,0]
	v_pk_mul_f32 v[60:61], v[60:61], v[2:3] op_sel_hi:[1,0]
	v_pk_mul_f32 v[58:59], v[58:59], v[2:3] op_sel_hi:[1,0]
	v_pk_mul_f32 v[56:57], v[56:57], v[2:3] op_sel_hi:[1,0]
	v_pk_mul_f32 v[54:55], v[54:55], v[2:3] op_sel_hi:[1,0]
	v_pk_mul_f32 v[52:53], v[52:53], v[2:3] op_sel_hi:[1,0]
	v_pk_mul_f32 v[50:51], v[50:51], v[2:3] op_sel_hi:[1,0]
	v_pk_mul_f32 v[48:49], v[48:49], v[2:3] op_sel_hi:[1,0]
	v_pk_mul_f32 v[46:47], v[46:47], v[2:3] op_sel_hi:[1,0]
	v_pk_mul_f32 v[44:45], v[44:45], v[2:3] op_sel_hi:[1,0]
	v_pk_mul_f32 v[42:43], v[42:43], v[2:3] op_sel_hi:[1,0]
	v_pk_mul_f32 v[40:41], v[40:41], v[2:3] op_sel_hi:[1,0]
	v_pk_mul_f32 v[38:39], v[38:39], v[2:3] op_sel_hi:[1,0]
	v_pk_mul_f32 v[36:37], v[36:37], v[2:3] op_sel_hi:[1,0]
	v_pk_mul_f32 v[34:35], v[34:35], v[2:3] op_sel_hi:[1,0]
	v_pk_mul_f32 v[32:33], v[32:33], v[2:3] op_sel_hi:[1,0]
	v_pk_mul_f32 v[30:31], v[30:31], v[2:3] op_sel_hi:[1,0]
	v_pk_mul_f32 v[28:29], v[28:29], v[2:3] op_sel_hi:[1,0]
	v_pk_mul_f32 v[26:27], v[26:27], v[2:3] op_sel_hi:[1,0]
	v_pk_mul_f32 v[24:25], v[24:25], v[2:3] op_sel_hi:[1,0]
	v_pk_mul_f32 v[22:23], v[22:23], v[2:3] op_sel_hi:[1,0]
	v_pk_mul_f32 v[20:21], v[20:21], v[2:3] op_sel_hi:[1,0]
	v_pk_mul_f32 v[18:19], v[18:19], v[2:3] op_sel_hi:[1,0]
	v_mul_f32_e32 v153, v153, v2
	s_branch .LBB0_1242
